# v010 + nt (non-temporal) hint on the read-once residual x loads of the P5 epilogue, to keep x1 resident in Infinity Cache for the next phase
# baseline (speedup 1.0000x reference)
;     __device__ __forceinline__ void operator()(const f32x4 (&acc)[2][2][4][2], const Unit& u, int wr, int wc, int fr, int fq) const {
;         const int row0 = u.pm * BM + wr * 64 + fr, col0 = u.pn * BM + wc * 32 + 4 * fq;
;         const float* gb = gate + (size_t)(u.pm >> 3) * NIN;
;         f32x4 gv[2][2];
; #pragma unroll
;         for (int bj = 0; bj < 2; ++bj)
; #pragma unroll
;             for (int n = 0; n < 2; ++n) gv[bj][n] = *(const f32x4*)(gb + col0 + bj * HALF + n * 16);
; #pragma unroll
;         for (int ai = 0; ai < 2; ++ai)
; #pragma unroll
;             for (int m = 0; m < 4; ++m) { const size_t off = (size_t)(row0 + ai * HALF + m * 16) * 2048 + col0;
; #pragma unroll
;                 for (int bj = 0; bj < 2; ++bj)
; #pragma unroll
;                     for (int n = 0; n < 2; ++n) { const f32x4 bs = *(const f32x4*)(base + off + bj * HALF + n * 16);
;                         *(f32x4*)(out + off + bj * HALF + n * 16) = bs + gv[bj][n] * acc[ai][bj][m][n]; } }
;     }
.LBB0_616:
	v_lshl_add_u32 v178, s38, 8, v158
	v_lshl_or_b32 v176, s55, 8, v160
	s_ashr_i32 s29, s38, 3
	v_ashrrev_i32_e32 v179, 31, v178
	s_mul_hi_i32 s31, s29, 0xc000
	s_mul_i32 s29, s29, 0xc000
	v_ashrrev_i32_e32 v177, 31, v176
	v_lshlrev_b64 v[130:131], 11, v[178:179]
	s_add_u32 s40, s50, s29
	v_lshl_add_u64 v[130:131], v[130:131], 0, v[176:177]
	s_addc_u32 s41, s51, s31
	v_lshlrev_b64 v[156:157], 2, v[130:131]
	v_lshl_add_u64 v[128:129], v[176:177], 2, s[40:41]
	global_load_dwordx4 v[140:143], v[128:129], off
	global_load_dwordx4 v[136:139], v[128:129], off offset:64
	global_load_dwordx4 v[132:135], v[128:129], off offset:512
	s_nop 0
	global_load_dwordx4 v[128:131], v[128:129], off offset:576
	v_add_u32_e32 v192, 0x20000, v156
	v_add_u32_e32 v193, 0x40000, v156
	v_add_u32_e32 v224, 0x60000, v156
	v_add_u32_e32 v225, 0x100000, v156
	v_add_u32_e32 v226, 0x120000, v156
	v_add_u32_e32 v227, 0x140000, v156
	v_add_u32_e32 v228, 0x160000, v156
	s_andn2_b64 vcc, exec, s[4:5]
	s_mov_b64 s[4:5], -1
	global_load_dwordx4 v[172:175], v156, s[6:7] nt
	global_load_dwordx4 v[176:179], v156, s[6:7] offset:64 nt
	global_load_dwordx4 v[180:183], v156, s[6:7] offset:512 nt
	global_load_dwordx4 v[184:187], v156, s[6:7] offset:576 nt
	global_load_dwordx4 v[188:191], v192, s[6:7] nt
	global_load_dwordx4 v[196:199], v192, s[6:7] offset:64 nt
	global_load_dwordx4 v[200:203], v192, s[6:7] offset:512 nt
	global_load_dwordx4 v[204:207], v192, s[6:7] offset:576 nt
	global_load_dwordx4 v[208:211], v193, s[6:7] nt
	global_load_dwordx4 v[212:215], v193, s[6:7] offset:64 nt
	global_load_dwordx4 v[216:219], v193, s[6:7] offset:512 nt
	global_load_dwordx4 v[220:223], v193, s[6:7] offset:576 nt
	s_waitcnt vmcnt(11)
	v_pk_fma_f32 v[126:127], v[126:127], v[142:143], v[174:175]
	v_pk_fma_f32 v[124:125], v[124:125], v[140:141], v[172:173]
	global_store_dwordx4 v156, v[124:127], s[8:9]
	s_waitcnt vmcnt(11)
	v_pk_fma_f32 v[122:123], v[122:123], v[138:139], v[178:179]
	v_pk_fma_f32 v[120:121], v[120:121], v[136:137], v[176:177]
	global_store_dwordx4 v156, v[120:123], s[8:9] offset:64
	s_waitcnt vmcnt(11)
	v_pk_fma_f32 v[118:119], v[118:119], v[134:135], v[182:183]
	v_pk_fma_f32 v[116:117], v[116:117], v[132:133], v[180:181]
	global_store_dwordx4 v156, v[116:119], s[8:9] offset:512
	s_waitcnt vmcnt(11)
	v_pk_fma_f32 v[106:107], v[106:107], v[130:131], v[186:187]
	v_pk_fma_f32 v[104:105], v[104:105], v[128:129], v[184:185]
	global_store_dwordx4 v156, v[104:107], s[8:9] offset:576
	global_load_dwordx4 v[172:175], v224, s[6:7] nt
	global_load_dwordx4 v[176:179], v224, s[6:7] offset:64 nt
	global_load_dwordx4 v[180:183], v224, s[6:7] offset:512 nt
	global_load_dwordx4 v[184:187], v224, s[6:7] offset:576 nt
	global_load_dwordx4 v[124:127], v225, s[6:7] nt
	global_load_dwordx4 v[120:123], v225, s[6:7] offset:64 nt
	global_load_dwordx4 v[116:119], v225, s[6:7] offset:512 nt
	global_load_dwordx4 v[104:107], v225, s[6:7] offset:576 nt
	s_waitcnt vmcnt(19)
	v_pk_fma_f32 v[114:115], v[114:115], v[142:143], v[190:191]
	v_pk_fma_f32 v[112:113], v[112:113], v[140:141], v[188:189]
	global_store_dwordx4 v192, v[112:115], s[8:9]
	s_waitcnt vmcnt(19)
	v_pk_fma_f32 v[110:111], v[110:111], v[138:139], v[198:199]
	v_pk_fma_f32 v[108:109], v[108:109], v[136:137], v[196:197]
	global_store_dwordx4 v192, v[108:111], s[8:9] offset:64
	s_waitcnt vmcnt(19)
	v_pk_fma_f32 v[102:103], v[102:103], v[134:135], v[202:203]
	v_pk_fma_f32 v[100:101], v[100:101], v[132:133], v[200:201]
	global_store_dwordx4 v192, v[100:103], s[8:9] offset:512
	s_waitcnt vmcnt(19)
	v_pk_fma_f32 v[90:91], v[90:91], v[130:131], v[206:207]
	v_pk_fma_f32 v[88:89], v[88:89], v[128:129], v[204:205]
	global_store_dwordx4 v192, v[88:91], s[8:9] offset:576
	global_load_dwordx4 v[188:191], v226, s[6:7] nt
	global_load_dwordx4 v[196:199], v226, s[6:7] offset:64 nt
	global_load_dwordx4 v[200:203], v226, s[6:7] offset:512 nt
	global_load_dwordx4 v[204:207], v226, s[6:7] offset:576 nt
	global_load_dwordx4 v[112:115], v227, s[6:7] nt
	global_load_dwordx4 v[108:111], v227, s[6:7] offset:64 nt
	global_load_dwordx4 v[100:103], v227, s[6:7] offset:512 nt
	global_load_dwordx4 v[88:91], v227, s[6:7] offset:576 nt
	s_waitcnt vmcnt(27)
	v_pk_fma_f32 v[98:99], v[98:99], v[142:143], v[210:211]
	v_pk_fma_f32 v[96:97], v[96:97], v[140:141], v[208:209]
	global_store_dwordx4 v193, v[96:99], s[8:9]
	s_waitcnt vmcnt(27)
	v_pk_fma_f32 v[94:95], v[94:95], v[138:139], v[214:215]
	v_pk_fma_f32 v[92:93], v[92:93], v[136:137], v[212:213]
	global_store_dwordx4 v193, v[92:95], s[8:9] offset:64
	s_waitcnt vmcnt(27)
;     __device__ __forceinline__ void operator()(const f32x4 (&acc)[2][2][4][2], const Unit& u, int wr, int wc, int fr, int fq) const {
;     ...
;             for (int m = 0; m < 4; ++m) { const size_t off = (size_t)(row0 + ai * HALF + m * 16) * 2048 + col0;
; #pragma unroll
;                 for (int bj = 0; bj < 2; ++bj)
; #pragma unroll
;                     for (int n = 0; n < 2; ++n) { const f32x4 bs = *(const f32x4*)(base + off + bj * HALF + n * 16);
;                         *(f32x4*)(out + off + bj * HALF + n * 16) = bs + gv[bj][n] * acc[ai][bj][m][n]; } }
	v_pk_fma_f32 v[86:87], v[86:87], v[134:135], v[218:219]
	v_pk_fma_f32 v[84:85], v[84:85], v[132:133], v[216:217]
	global_store_dwordx4 v193, v[84:87], s[8:9] offset:512
	s_waitcnt vmcnt(27)
	v_pk_fma_f32 v[74:75], v[74:75], v[130:131], v[222:223]
	v_pk_fma_f32 v[72:73], v[72:73], v[128:129], v[220:221]
	global_store_dwordx4 v193, v[72:75], s[8:9] offset:576
	global_load_dwordx4 v[208:211], v228, s[6:7] nt
	global_load_dwordx4 v[212:215], v228, s[6:7] offset:64 nt
	global_load_dwordx4 v[216:219], v228, s[6:7] offset:512 nt
	global_load_dwordx4 v[220:223], v228, s[6:7] offset:576 nt
	s_waitcnt vmcnt(27)
	v_pk_fma_f32 v[82:83], v[82:83], v[142:143], v[174:175]
	v_pk_fma_f32 v[80:81], v[80:81], v[140:141], v[172:173]
	global_store_dwordx4 v224, v[80:83], s[8:9]
	s_waitcnt vmcnt(27)
	v_pk_fma_f32 v[78:79], v[78:79], v[138:139], v[178:179]
	v_pk_fma_f32 v[76:77], v[76:77], v[136:137], v[176:177]
	global_store_dwordx4 v224, v[76:79], s[8:9] offset:64
	s_waitcnt vmcnt(27)
	v_pk_fma_f32 v[70:71], v[70:71], v[134:135], v[182:183]
	v_pk_fma_f32 v[68:69], v[68:69], v[132:133], v[180:181]
	global_store_dwordx4 v224, v[68:71], s[8:9] offset:512
	s_waitcnt vmcnt(27)
	v_pk_fma_f32 v[66:67], v[66:67], v[130:131], v[186:187]
	v_pk_fma_f32 v[64:65], v[64:65], v[128:129], v[184:185]
	global_store_dwordx4 v224, v[64:67], s[8:9] offset:576
	s_waitcnt vmcnt(27)
	v_pk_fma_f32 v[62:63], v[62:63], v[142:143], v[126:127]
	v_pk_fma_f32 v[60:61], v[60:61], v[140:141], v[124:125]
	global_store_dwordx4 v225, v[60:63], s[8:9]
	s_waitcnt vmcnt(27)
	v_pk_fma_f32 v[58:59], v[58:59], v[138:139], v[122:123]
	v_pk_fma_f32 v[56:57], v[56:57], v[136:137], v[120:121]
	global_store_dwordx4 v225, v[56:59], s[8:9] offset:64
	s_waitcnt vmcnt(27)
	v_pk_fma_f32 v[54:55], v[54:55], v[134:135], v[118:119]
	v_pk_fma_f32 v[52:53], v[52:53], v[132:133], v[116:117]
	global_store_dwordx4 v225, v[52:55], s[8:9] offset:512
	s_waitcnt vmcnt(27)
	v_pk_fma_f32 v[42:43], v[42:43], v[130:131], v[106:107]
	v_pk_fma_f32 v[40:41], v[40:41], v[128:129], v[104:105]
	global_store_dwordx4 v225, v[40:43], s[8:9] offset:576
	s_waitcnt vmcnt(23)
	v_pk_fma_f32 v[50:51], v[50:51], v[142:143], v[190:191]
	v_pk_fma_f32 v[48:49], v[48:49], v[140:141], v[188:189]
	global_store_dwordx4 v226, v[48:51], s[8:9]
	s_waitcnt vmcnt(23)
	v_pk_fma_f32 v[46:47], v[46:47], v[138:139], v[198:199]
	v_pk_fma_f32 v[44:45], v[44:45], v[136:137], v[196:197]
	global_store_dwordx4 v226, v[44:47], s[8:9] offset:64
	s_waitcnt vmcnt(23)
	v_pk_fma_f32 v[38:39], v[38:39], v[134:135], v[202:203]
	v_pk_fma_f32 v[36:37], v[36:37], v[132:133], v[200:201]
	global_store_dwordx4 v226, v[36:39], s[8:9] offset:512
	s_waitcnt vmcnt(23)
	v_pk_fma_f32 v[26:27], v[26:27], v[130:131], v[206:207]
	v_pk_fma_f32 v[24:25], v[24:25], v[128:129], v[204:205]
	global_store_dwordx4 v226, v[24:27], s[8:9] offset:576
	s_waitcnt vmcnt(23)
	v_pk_fma_f32 v[34:35], v[34:35], v[142:143], v[114:115]
	v_pk_fma_f32 v[32:33], v[32:33], v[140:141], v[112:113]
	global_store_dwordx4 v227, v[32:35], s[8:9]
	s_waitcnt vmcnt(23)
	v_pk_fma_f32 v[30:31], v[30:31], v[138:139], v[110:111]
	v_pk_fma_f32 v[28:29], v[28:29], v[136:137], v[108:109]
	global_store_dwordx4 v227, v[28:31], s[8:9] offset:64
	s_waitcnt vmcnt(23)
	v_pk_fma_f32 v[22:23], v[22:23], v[134:135], v[102:103]
	v_pk_fma_f32 v[20:21], v[20:21], v[132:133], v[100:101]
	global_store_dwordx4 v227, v[20:23], s[8:9] offset:512
	s_waitcnt vmcnt(23)
	v_pk_fma_f32 v[10:11], v[10:11], v[130:131], v[90:91]
	v_pk_fma_f32 v[8:9], v[8:9], v[128:129], v[88:89]
	global_store_dwordx4 v227, v[8:11], s[8:9] offset:576
	s_waitcnt vmcnt(19)
	v_pk_fma_f32 v[18:19], v[18:19], v[142:143], v[210:211]
	v_pk_fma_f32 v[16:17], v[16:17], v[140:141], v[208:209]
	global_store_dwordx4 v228, v[16:19], s[8:9]
	s_waitcnt vmcnt(19)
	v_pk_fma_f32 v[14:15], v[14:15], v[138:139], v[214:215]
	v_pk_fma_f32 v[12:13], v[12:13], v[136:137], v[212:213]
	global_store_dwordx4 v228, v[12:15], s[8:9] offset:64
	s_waitcnt vmcnt(19)
	v_pk_fma_f32 v[6:7], v[6:7], v[134:135], v[218:219]
	v_pk_fma_f32 v[4:5], v[4:5], v[132:133], v[216:217]
	global_store_dwordx4 v228, v[4:7], s[8:9] offset:512
	s_waitcnt vmcnt(19)
	v_pk_fma_f32 v[2:3], v[2:3], v[130:131], v[222:223]
	v_pk_fma_f32 v[0:1], v[0:1], v[128:129], v[220:221]
	global_store_dwordx4 v228, v[0:3], s[8:9] offset:576
	s_cbranch_vccnz .LBB0_605
	s_andn2_b64 vcc, exec, s[16:17]
	s_cbranch_vccnz .LBB0_604
	s_barrier
	s_branch .LBB0_604
